# prep phase loads pipelined (12-deep ring) + conv fix-up phase rewritten: one (boundary, 8-channel) item per thread, all loads in flight
# speedup vs baseline: 1.0050x; 1.0014x over previous
; __device__ __forceinline__ unsigned cvt_pk_bf16(float lo, float hi) { const f32x2v v = {lo, hi}; const b16x2v r = __builtin_convertvector(v, b16x2v); return __builtin_bit_cast(unsigned, r); }
; __device__ __forceinline__ float silu_f(float v) { return v / (1.0f + fexp2(-v * LOG2E)); }
; __device__ __forceinline__ int opaque_tid() { int t = (int)threadIdx.x; asm volatile("" : "+v"(t)); return t; }
; __device__ void conv_fixup(const Params& p) {
;     unsigned char* ws = p.ws;
;     const float* hu = (const float*)(ws + OFF_U); bf16_t* gout = (bf16_t*)(ws + OFF_G);
;     for (int task = blockIdx.x * 512 + opaque_tid(); task < 128 * DFF; task += gridDim.x * 512) {
;         const int bd = task / DFF, c = task - bd * DFF, pm = bd >> 1, hb = bd & 1;
;         if (hb == 0 && (pm & 15) == 0) continue;
;         const int rp = (hb == 0) ? ((pm - 1) * 8 + 6) : (pm * 8 + 2), rc = pm * 8 + 4 * hb;
;         float ug[4], uu[4];
;         ug[0] = hu[((size_t)((rp + 0) * 2 + 0)) * DFF + c]; ug[1] = hu[((size_t)((rp + 1) * 2 + 0)) * DFF + c];
;         ug[2] = hu[((size_t)((rc + 0) * 2 + 0)) * DFF + c]; ug[3] = hu[((size_t)((rc + 1) * 2 + 0)) * DFF + c];
;         uu[0] = hu[((size_t)((rp + 0) * 2 + 1)) * DFF + c]; uu[1] = hu[((size_t)((rp + 1) * 2 + 1)) * DFF + c];
;         uu[2] = hu[((size_t)((rc + 0) * 2 + 1)) * DFF + c]; uu[3] = hu[((size_t)((rc + 1) * 2 + 1)) * DFF + c];
;         const float wg0 = p.conv_w[c], wg1 = p.conv_w[11008 + c], wg2 = p.conv_w[22016 + c], wu0 = p.conv_w[DFF + c], wu1 = p.conv_w[11008 + DFF + c], wu2 = p.conv_w[22016 + DFF + c];
;         const float bg = p.conv_b[c], bu = p.conv_b[DFF + c];
; #pragma unroll
;         for (int e = 0; e < 2; ++e) {
;             const float yg = bg + wg0 * ug[e] + wg1 * ug[e + 1] + wg2 * ug[e + 2];
;             const float yu = bu + wu0 * uu[e] + wu1 * uu[e + 1] + wu2 * uu[e + 2];
;             const float r = silu_f(yg) * yu;
;             gout[(size_t)(pm * 256 + 128 * hb + e) * DFF + c] = (bf16_t)(cvt_pk_bf16(r, r) & 0xffffu);
;         }
;     }
; }
.LBB0_38:
	s_and_b64 vcc, exec, s[0:1]
	s_mov_b64 s[0:1], 0
	v_writelane_b32 v254, s0, 47
	s_mov_b64 s[58:59], 0
	s_nop 0
	v_writelane_b32 v254, s1, 48
	s_mov_b64 s[0:1], 0
	s_cbranch_vccz .LBB0_50
	v_readlane_b32 s36, v251, 0
	v_readlane_b32 s0, v254, 39
	v_readlane_b32 s38, v251, 2
	v_readlane_b32 s39, v251, 3
	s_cmp_gt_i32 s0, 10
	s_mov_b64 s[6:7], -1
	s_mov_b64 s[58:59], s[38:39]
	s_mov_b64 s[0:1], -1
	v_readlane_b32 s37, v251, 1
	v_readlane_b32 s40, v251, 4
	v_readlane_b32 s41, v251, 5
	v_readlane_b32 s42, v251, 6
	v_readlane_b32 s43, v251, 7
	s_cbranch_scc0 .LBB0_46
	v_mov_b32_e32 v0, v212
	s_mov_b32 s0, 0x15800
	v_add_u32_e32 v0, s35, v0
	v_cmp_gt_i32_e32 vcc, s0, v0
	s_and_saveexec_b64 s[0:1], vcc
	s_movk_i32 s16, 0x5000
	s_cbranch_execz .LBB0_45
	s_mov_b32 s10, 0x5f417d1
	v_lshrrev_b32_e32 v1, 4, v0
	v_mul_hi_u32 v1, v1, s10
	v_mul_u32_u24_e32 v2, 0x2b0, v1
	v_sub_u32_e32 v2, v0, v2
	v_lshrrev_b32_e32 v4, 1, v1
	v_and_b32_e32 v5, 1, v1
	v_and_b32_e32 v6, 15, v4
	v_or_b32_e32 v6, v6, v5
	v_cmp_ne_u32_e32 vcc, 0, v6
	s_and_b64 exec, exec, vcc
	s_cbranch_execz .LBB0_45
	v_lshlrev_b32_e32 v7, 3, v4
	v_lshl_add_u32 v8, v5, 2, v7
	v_lshlrev_b32_e32 v9, 2, v5
	v_add_u32_e32 v9, -2, v9
	v_add_u32_e32 v9, v7, v9
	v_lshlrev_b32_e32 v10, 5, v2
	s_movk_i32 s2, 0x5600
	v_lshlrev_b32_e32 v11, 1, v9
	v_mad_u32_u24 v11, v11, s2, v10
	v_lshlrev_b32_e32 v12, 1, v8
	v_mad_u32_u24 v12, v12, s2, v10
	s_add_u32 s10, s68, 0x5600
	s_addc_u32 s11, s69, 0
	s_add_u32 s12, s68, 0xac00
	s_addc_u32 s13, s69, 0
	s_add_u32 s14, s68, 0x10200
	s_addc_u32 s15, s69, 0
	global_load_dwordx4 v[16:19], v11, s[68:69]
	global_load_dwordx4 v[20:23], v11, s[68:69] offset:16
	global_load_dwordx4 v[24:27], v11, s[10:11]
	global_load_dwordx4 v[28:31], v11, s[10:11] offset:16
	global_load_dwordx4 v[32:35], v11, s[12:13]
	global_load_dwordx4 v[36:39], v11, s[12:13] offset:16
	global_load_dwordx4 v[40:43], v11, s[14:15]
	global_load_dwordx4 v[44:47], v11, s[14:15] offset:16
	global_load_dwordx4 v[48:51], v12, s[68:69]
	global_load_dwordx4 v[52:55], v12, s[68:69] offset:16
	global_load_dwordx4 v[56:59], v12, s[10:11]
	global_load_dwordx4 v[60:63], v12, s[10:11] offset:16
	global_load_dwordx4 v[64:67], v12, s[12:13]
	global_load_dwordx4 v[68:71], v12, s[12:13] offset:16
	global_load_dwordx4 v[72:75], v12, s[14:15]
	global_load_dwordx4 v[76:79], v12, s[14:15] offset:16
	v_readlane_b32 s36, v251, 0
	v_readlane_b32 s37, v251, 1
	v_readlane_b32 s38, v251, 2
	v_readlane_b32 s39, v251, 3
	v_add_u32_e32 v81, 0x5600, v10
	v_add_u32_e32 v82, 0xac00, v10
	v_add_u32_e32 v83, 0x10200, v10
	v_add_u32_e32 v84, 0x15800, v10
	v_add_u32_e32 v85, 0x1ae00, v10
	global_load_dwordx4 v[88:91], v10, s[36:37]
	global_load_dwordx4 v[92:95], v10, s[36:37] offset:16
	global_load_dwordx4 v[96:99], v81, s[36:37]
	global_load_dwordx4 v[100:103], v81, s[36:37] offset:16
	global_load_dwordx4 v[104:107], v82, s[36:37]
	global_load_dwordx4 v[108:111], v82, s[36:37] offset:16
	global_load_dwordx4 v[112:115], v83, s[36:37]
	global_load_dwordx4 v[116:119], v83, s[36:37] offset:16
	global_load_dwordx4 v[120:123], v84, s[36:37]
	global_load_dwordx4 v[124:127], v84, s[36:37] offset:16
	global_load_dwordx4 v[128:131], v85, s[36:37]
	global_load_dwordx4 v[132:135], v85, s[36:37] offset:16
	global_load_dwordx4 v[136:139], v10, s[38:39]
	global_load_dwordx4 v[140:143], v10, s[38:39] offset:16
	global_load_dwordx4 v[144:147], v81, s[38:39]
	global_load_dwordx4 v[148:151], v81, s[38:39] offset:16
	v_lshlrev_b32_e32 v13, 8, v4
	v_lshl_or_b32 v13, v5, 7, v13
	v_lshlrev_b32_e32 v14, 4, v2
	s_movk_i32 s2, 0x2b00
	v_mad_u32_u24 v14, v13, s2, v14
	v_add_u32_e32 v15, 0x2b00, v14
	v_readlane_b32 s2, v251, 10
	v_readlane_b32 s3, v251, 11
	s_waitcnt vmcnt(0)
; __device__ __forceinline__ unsigned cvt_pk_bf16(float lo, float hi) { const f32x2v v = {lo, hi}; const b16x2v r = __builtin_convertvector(v, b16x2v); return __builtin_bit_cast(unsigned, r); }
; __device__ __forceinline__ float silu_f(float v) { return v / (1.0f + fexp2(-v * LOG2E)); }
; __device__ void conv_fixup(const Params& p) {
;     ...
;         const float wg0 = p.conv_w[c], wg1 = p.conv_w[11008 + c], wg2 = p.conv_w[22016 + c], wu0 = p.conv_w[DFF + c], wu1 = p.conv_w[11008 + DFF + c], wu2 = p.conv_w[22016 + DFF + c];
;         const float bg = p.conv_b[c], bu = p.conv_b[DFF + c];
; #pragma unroll
;         for (int e = 0; e < 2; ++e) {
;             const float yg = bg + wg0 * ug[e] + wg1 * ug[e + 1] + wg2 * ug[e + 2];
;             const float yu = bu + wu0 * uu[e] + wu1 * uu[e + 1] + wu2 * uu[e + 2];
;             const float r = silu_f(yg) * yu;
;             gout[(size_t)(pm * 256 + 128 * hb + e) * DFF + c] = (bf16_t)(cvt_pk_bf16(r, r) & 0xffffu);
;         }
	v_fma_f32 v152, v16, v88, v136
	v_fma_f32 v160, v24, v96, v144
	v_fma_f32 v153, v17, v89, v137
	v_fma_f32 v161, v25, v97, v145
	v_fma_f32 v154, v18, v90, v138
	v_fma_f32 v162, v26, v98, v146
	v_fma_f32 v155, v19, v91, v139
	v_fma_f32 v163, v27, v99, v147
	v_fma_f32 v156, v20, v92, v140
	v_fma_f32 v164, v28, v100, v148
	v_fma_f32 v157, v21, v93, v141
	v_fma_f32 v165, v29, v101, v149
	v_fma_f32 v158, v22, v94, v142
	v_fma_f32 v166, v30, v102, v150
	v_fma_f32 v159, v23, v95, v143
	v_fma_f32 v167, v31, v103, v151
	v_fmac_f32_e32 v152, v32, v104
	v_fmac_f32_e32 v160, v40, v112
	v_fmac_f32_e32 v153, v33, v105
	v_fmac_f32_e32 v161, v41, v113
	v_fmac_f32_e32 v154, v34, v106
	v_fmac_f32_e32 v162, v42, v114
	v_fmac_f32_e32 v155, v35, v107
	v_fmac_f32_e32 v163, v43, v115
	v_fmac_f32_e32 v156, v36, v108
	v_fmac_f32_e32 v164, v44, v116
	v_fmac_f32_e32 v157, v37, v109
	v_fmac_f32_e32 v165, v45, v117
	v_fmac_f32_e32 v158, v38, v110
	v_fmac_f32_e32 v166, v46, v118
	v_fmac_f32_e32 v159, v39, v111
	v_fmac_f32_e32 v167, v47, v119
	v_fmac_f32_e32 v152, v48, v120
	v_fmac_f32_e32 v160, v56, v128
	v_fmac_f32_e32 v153, v49, v121
	v_fmac_f32_e32 v161, v57, v129
	v_fmac_f32_e32 v154, v50, v122
	v_fmac_f32_e32 v162, v58, v130
	v_fmac_f32_e32 v155, v51, v123
	v_fmac_f32_e32 v163, v59, v131
	v_fmac_f32_e32 v156, v52, v124
	v_fmac_f32_e32 v164, v60, v132
	v_fmac_f32_e32 v157, v53, v125
	v_fmac_f32_e32 v165, v61, v133
	v_fmac_f32_e32 v158, v54, v126
	v_fmac_f32_e32 v166, v62, v134
	v_fmac_f32_e32 v159, v55, v127
	v_fmac_f32_e32 v167, v63, v135
	v_mul_f32_e32 v168, 0xbfb8aa3b, v152
	v_mul_f32_e32 v169, 0xbfb8aa3b, v153
	v_mul_f32_e32 v170, 0xbfb8aa3b, v154
	v_mul_f32_e32 v171, 0xbfb8aa3b, v155
	v_mul_f32_e32 v172, 0xbfb8aa3b, v156
	v_mul_f32_e32 v173, 0xbfb8aa3b, v157
	v_mul_f32_e32 v174, 0xbfb8aa3b, v158
	v_mul_f32_e32 v175, 0xbfb8aa3b, v159
	v_exp_f32_e32 v168, v168
	v_exp_f32_e32 v169, v169
	v_exp_f32_e32 v170, v170
	v_exp_f32_e32 v171, v171
	v_exp_f32_e32 v172, v172
	v_exp_f32_e32 v173, v173
	v_exp_f32_e32 v174, v174
	v_exp_f32_e32 v175, v175
	s_nop 0
	v_add_f32_e32 v168, 1.0, v168
	v_add_f32_e32 v169, 1.0, v169
	v_add_f32_e32 v170, 1.0, v170
	v_add_f32_e32 v171, 1.0, v171
	v_add_f32_e32 v172, 1.0, v172
	v_add_f32_e32 v173, 1.0, v173
	v_add_f32_e32 v174, 1.0, v174
	v_add_f32_e32 v175, 1.0, v175
	v_rcp_f32_e32 v168, v168
	v_rcp_f32_e32 v169, v169
	v_rcp_f32_e32 v170, v170
	v_rcp_f32_e32 v171, v171
	v_rcp_f32_e32 v172, v172
	v_rcp_f32_e32 v173, v173
	v_rcp_f32_e32 v174, v174
	v_rcp_f32_e32 v175, v175
	s_nop 0
	v_mul_f32_e32 v152, v152, v168
	v_mul_f32_e32 v153, v153, v169
	v_mul_f32_e32 v154, v154, v170
	v_mul_f32_e32 v155, v155, v171
	v_mul_f32_e32 v156, v156, v172
	v_mul_f32_e32 v157, v157, v173
	v_mul_f32_e32 v158, v158, v174
	v_mul_f32_e32 v159, v159, v175
	v_mul_f32_e32 v152, v160, v152
	v_mul_f32_e32 v153, v161, v153
	v_mul_f32_e32 v154, v162, v154
	v_mul_f32_e32 v155, v163, v155
	v_mul_f32_e32 v156, v164, v156
	v_mul_f32_e32 v157, v165, v157
	v_mul_f32_e32 v158, v166, v158
	v_mul_f32_e32 v159, v167, v159
	v_cvt_pk_bf16_f32 v176, v152, v153
	v_cvt_pk_bf16_f32 v177, v154, v155
	v_cvt_pk_bf16_f32 v178, v156, v157
	v_cvt_pk_bf16_f32 v179, v158, v159
	global_store_dwordx4 v14, v[176:179], s[2:3]
	v_fma_f32 v152, v32, v88, v136
	v_fma_f32 v160, v40, v96, v144
	v_fma_f32 v153, v33, v89, v137
	v_fma_f32 v161, v41, v97, v145
	v_fma_f32 v154, v34, v90, v138
	v_fma_f32 v162, v42, v98, v146
	v_fma_f32 v155, v35, v91, v139
	v_fma_f32 v163, v43, v99, v147
	v_fma_f32 v156, v36, v92, v140
	v_fma_f32 v164, v44, v100, v148
	v_fma_f32 v157, v37, v93, v141
	v_fma_f32 v165, v45, v101, v149
	v_fma_f32 v158, v38, v94, v142
	v_fma_f32 v166, v46, v102, v150
	v_fma_f32 v159, v39, v95, v143
	v_fma_f32 v167, v47, v103, v151
	v_fmac_f32_e32 v152, v48, v104
	v_fmac_f32_e32 v160, v56, v112
	v_fmac_f32_e32 v153, v49, v105
	v_fmac_f32_e32 v161, v57, v113
	v_fmac_f32_e32 v154, v50, v106
	v_fmac_f32_e32 v162, v58, v114
	v_fmac_f32_e32 v155, v51, v107
	v_fmac_f32_e32 v163, v59, v115
	v_fmac_f32_e32 v156, v52, v108
	v_fmac_f32_e32 v164, v60, v116
	v_fmac_f32_e32 v157, v53, v109
	v_fmac_f32_e32 v165, v61, v117
	v_fmac_f32_e32 v158, v54, v110
	v_fmac_f32_e32 v166, v62, v118
	v_fmac_f32_e32 v159, v55, v111
	v_fmac_f32_e32 v167, v63, v119
	v_fmac_f32_e32 v152, v64, v120
	v_fmac_f32_e32 v160, v72, v128
	v_fmac_f32_e32 v153, v65, v121
	v_fmac_f32_e32 v161, v73, v129
	v_fmac_f32_e32 v154, v66, v122
	v_fmac_f32_e32 v162, v74, v130
	v_fmac_f32_e32 v155, v67, v123
	v_fmac_f32_e32 v163, v75, v131
	v_fmac_f32_e32 v156, v68, v124
	v_fmac_f32_e32 v164, v76, v132
	v_fmac_f32_e32 v157, v69, v125
	v_fmac_f32_e32 v165, v77, v133
	v_fmac_f32_e32 v158, v70, v126
	v_fmac_f32_e32 v166, v78, v134
	v_fmac_f32_e32 v159, v71, v127
	v_fmac_f32_e32 v167, v79, v135
	v_mul_f32_e32 v168, 0xbfb8aa3b, v152
	v_mul_f32_e32 v169, 0xbfb8aa3b, v153
	v_mul_f32_e32 v170, 0xbfb8aa3b, v154
	v_mul_f32_e32 v171, 0xbfb8aa3b, v155
	v_mul_f32_e32 v172, 0xbfb8aa3b, v156
	v_mul_f32_e32 v173, 0xbfb8aa3b, v157
	v_mul_f32_e32 v174, 0xbfb8aa3b, v158
	v_mul_f32_e32 v175, 0xbfb8aa3b, v159
	v_exp_f32_e32 v168, v168
	v_exp_f32_e32 v169, v169
	v_exp_f32_e32 v170, v170
	v_exp_f32_e32 v171, v171
	v_exp_f32_e32 v172, v172
	v_exp_f32_e32 v173, v173
	v_exp_f32_e32 v174, v174
	v_exp_f32_e32 v175, v175
	s_nop 0
	v_add_f32_e32 v168, 1.0, v168
	v_add_f32_e32 v169, 1.0, v169
	v_add_f32_e32 v170, 1.0, v170
	v_add_f32_e32 v171, 1.0, v171
	v_add_f32_e32 v172, 1.0, v172
	v_add_f32_e32 v173, 1.0, v173
	v_add_f32_e32 v174, 1.0, v174
	v_add_f32_e32 v175, 1.0, v175
	v_rcp_f32_e32 v168, v168
	v_rcp_f32_e32 v169, v169
	v_rcp_f32_e32 v170, v170
	v_rcp_f32_e32 v171, v171
	v_rcp_f32_e32 v172, v172
	v_rcp_f32_e32 v173, v173
	v_rcp_f32_e32 v174, v174
	v_rcp_f32_e32 v175, v175
	s_nop 0
	v_mul_f32_e32 v152, v152, v168
	v_mul_f32_e32 v153, v153, v169
	v_mul_f32_e32 v154, v154, v170
	v_mul_f32_e32 v155, v155, v171
	v_mul_f32_e32 v156, v156, v172
	v_mul_f32_e32 v157, v157, v173
	v_mul_f32_e32 v158, v158, v174
	v_mul_f32_e32 v159, v159, v175
	v_mul_f32_e32 v152, v160, v152
	v_mul_f32_e32 v153, v161, v153
	v_mul_f32_e32 v154, v162, v154
	v_mul_f32_e32 v155, v163, v155
	v_mul_f32_e32 v156, v164, v156
	v_mul_f32_e32 v157, v165, v157
	v_mul_f32_e32 v158, v166, v158
	v_mul_f32_e32 v159, v167, v159
	v_cvt_pk_bf16_f32 v180, v152, v153
	v_cvt_pk_bf16_f32 v181, v154, v155
	v_cvt_pk_bf16_f32 v182, v156, v157
	v_cvt_pk_bf16_f32 v183, v158, v159
	global_store_dwordx4 v15, v[180:183], s[2:3]

; __device__ __forceinline__ unsigned cvt_pk_bf16(float lo, float hi) { const f32x2v v = {lo, hi}; const b16x2v r = __builtin_convertvector(v, b16x2v); return __builtin_bit_cast(unsigned, r); }
; __device__ __forceinline__ f32x4 mfma16(bf16x8 a, bf16x8 b, f32x4 c) { return __builtin_amdgcn_mfma_f32_16x16x32_bf16(a, b, c, 0, 0, 0); }
; __device__ void prep_phase(const Params& p, unsigned char* smem_g) {
;     ...
;     for (int ch = blockIdx.x; ch < T_TOK / 64; ch += gridDim.x) {
;         const int t0 = ch * 64;
;         const int wk = (wid + (int)blockIdx.x) & 7, mrot = ((int)blockIdx.x >> 3) & 3;
;         bf16x8 bfr[8];
; #pragma unroll
;         for (int ks = 0; ks < 8; ++ks) {
;             float v[8];
; #pragma unroll
;             for (int e = 0; e < 8; ++e) v[e] = p.w_in[(size_t)(256 * wk + 32 * ks + 8 * g + e) * 6160 + 3072 + idx];
;             u32x4 w; w.x = cvt_pk_bf16(v[0], v[1]); w.y = cvt_pk_bf16(v[2], v[3]); w.z = cvt_pk_bf16(v[4], v[5]); w.w = cvt_pk_bf16(v[6], v[7]);
;             bfr[ks] = __builtin_bit_cast(bf16x8, w);
;         }
;         f32x4 acc[4];
; #pragma unroll
;         for (int mt = 0; mt < 4; ++mt) {
;             acc[mt] = (f32x4){0.f, 0.f, 0.f, 0.f};
; #pragma unroll
;             for (int ks = 0; ks < 8; ++ks) {
;                 const size_t off = (size_t)(t0 + 16 * ((mt + mrot) & 3) + idx) * DM + 256 * wk + 32 * ks + 8 * g;
;                 const f32x4 a = *(const f32x4*)(p.x + off), b = *(const f32x4*)(p.x + off + 4);
;                 u32x4 w; w.x = cvt_pk_bf16(a[0], a[1]); w.y = cvt_pk_bf16(a[2], a[3]); w.z = cvt_pk_bf16(b[0], b[1]); w.w = cvt_pk_bf16(b[2], b[3]);
;                 *(u32x4*)(xb + off) = w;
;                 acc[mt] = mfma16(__builtin_bit_cast(bf16x8, w), bfr[ks], acc[mt]);
;             }
;         }
.LBB0_142:
	s_lshl_b32 s0, s3, 6
	s_mov_b32 s4, 0
	s_add_i32 s5, 0, 0x8000
	global_load_dword v52, v[52:53], off
	global_load_dword v54, v[54:55], off
	global_load_dword v56, v[56:57], off
	global_load_dword v58, v[58:59], off
	global_load_dword v60, v[60:61], off
	global_load_dword v62, v[62:63], off
	global_load_dword v64, v[64:65], off
	global_load_dword v66, v[66:67], off
	global_load_dword v68, v[68:69], off
	global_load_dword v70, v[70:71], off
	global_load_dword v72, v[72:73], off
	global_load_dword v74, v[74:75], off
	global_load_dword v76, v[76:77], off
	global_load_dword v78, v[78:79], off
	global_load_dword v80, v[80:81], off
	global_load_dword v82, v[82:83], off
	global_load_dword v84, v[84:85], off
	global_load_dword v86, v[86:87], off
	global_load_dword v88, v[88:89], off
	global_load_dword v90, v[90:91], off
	global_load_dword v92, v[92:93], off
	global_load_dword v94, v[94:95], off
	global_load_dword v96, v[96:97], off
	global_load_dword v98, v[98:99], off
	global_load_dword v100, v[100:101], off
	global_load_dword v102, v[102:103], off
	global_load_dword v104, v[104:105], off
	global_load_dword v106, v[106:107], off
	global_load_dword v108, v[108:109], off
	global_load_dword v110, v[110:111], off
	global_load_dword v112, v[112:113], off
	global_load_dword v114, v[114:115], off
	global_load_dword v116, v[116:117], off
	global_load_dword v118, v[118:119], off
	global_load_dword v120, v[120:121], off
	global_load_dword v122, v[122:123], off
	global_load_dword v124, v[124:125], off
	global_load_dword v126, v[126:127], off
	global_load_dword v128, v[128:129], off
	global_load_dword v130, v[130:131], off
	global_load_dword v132, v[132:133], off
	global_load_dword v134, v[134:135], off
	global_load_dword v136, v[136:137], off
	global_load_dword v138, v[138:139], off
	global_load_dword v140, v[140:141], off
	global_load_dword v142, v[142:143], off
	global_load_dword v144, v[144:145], off
	global_load_dword v146, v[146:147], off
	global_load_dword v148, v[148:149], off
	global_load_dword v150, v[150:151], off
	global_load_dword v152, v[152:153], off
	global_load_dword v154, v[154:155], off
	global_load_dword v156, v[156:157], off
	global_load_dword v158, v[158:159], off
	global_load_dword v160, v[160:161], off
	global_load_dword v162, v[162:163], off
	global_load_dword v164, v[164:165], off
	global_load_dword v166, v[166:167], off
	global_load_dword v168, v[168:169], off
	global_load_dword v170, v[170:171], off
	global_load_dword v172, v[172:173], off
	global_load_dword v174, v[174:175], off
	global_load_dword v176, v[176:177], off
	global_load_dword v178, v[178:179], off
	s_waitcnt vmcnt(0)
	v_cvt_pk_bf16_f32 v32, v52, v54
	v_cvt_pk_bf16_f32 v33, v56, v58
	v_cvt_pk_bf16_f32 v34, v60, v62
	v_cvt_pk_bf16_f32 v35, v64, v66
	v_cvt_pk_bf16_f32 v28, v68, v70
	v_cvt_pk_bf16_f32 v29, v72, v74
	v_cvt_pk_bf16_f32 v30, v76, v78
	v_cvt_pk_bf16_f32 v31, v80, v82
	v_cvt_pk_bf16_f32 v24, v84, v86
	v_cvt_pk_bf16_f32 v25, v88, v90
	v_cvt_pk_bf16_f32 v26, v92, v94
	v_cvt_pk_bf16_f32 v27, v96, v98
	v_cvt_pk_bf16_f32 v20, v100, v102
	v_cvt_pk_bf16_f32 v21, v104, v106
	v_cvt_pk_bf16_f32 v22, v108, v110
	v_cvt_pk_bf16_f32 v23, v112, v114
	v_cvt_pk_bf16_f32 v16, v116, v118
	v_cvt_pk_bf16_f32 v17, v120, v122
	v_cvt_pk_bf16_f32 v18, v124, v126
	v_cvt_pk_bf16_f32 v19, v128, v130
	v_cvt_pk_bf16_f32 v12, v132, v134
	v_cvt_pk_bf16_f32 v13, v136, v138
	v_cvt_pk_bf16_f32 v14, v140, v142
	v_cvt_pk_bf16_f32 v15, v144, v146
	v_cvt_pk_bf16_f32 v8, v148, v150
	v_cvt_pk_bf16_f32 v9, v152, v154
	v_cvt_pk_bf16_f32 v10, v156, v158
	v_cvt_pk_bf16_f32 v11, v160, v162
	v_cvt_pk_bf16_f32 v4, v164, v166
	v_cvt_pk_bf16_f32 v5, v168, v170
	v_cvt_pk_bf16_f32 v6, v172, v174
	v_cvt_pk_bf16_f32 v7, v176, v178
	v_or_b32_e32 v244, s0, v229
	v_ashrrev_i32_e32 v245, 31, v244
	v_lshlrev_b64 v[244:245], 11, v[244:245]
	v_or_b32_e32 v244, v244, v48
	v_lshl_add_u64 v[148:149], v[244:245], 2, s[72:73]
	v_lshl_add_u64 v[156:157], v[244:245], 1, s[92:93]
	v_or_b32_e32 v244, s0, v230
	v_ashrrev_i32_e32 v245, 31, v244
	v_lshlrev_b64 v[244:245], 11, v[244:245]
	v_or_b32_e32 v244, v244, v48
	v_lshl_add_u64 v[150:151], v[244:245], 2, s[72:73]
	v_lshl_add_u64 v[158:159], v[244:245], 1, s[92:93]
	v_or_b32_e32 v244, s0, v231
	v_ashrrev_i32_e32 v245, 31, v244
	v_lshlrev_b64 v[244:245], 11, v[244:245]
	v_or_b32_e32 v244, v244, v48
	v_lshl_add_u64 v[152:153], v[244:245], 2, s[72:73]
	v_lshl_add_u64 v[160:161], v[244:245], 1, s[92:93]
	v_or_b32_e32 v244, s0, v234
	v_ashrrev_i32_e32 v245, 31, v244
	v_lshlrev_b64 v[244:245], 11, v[244:245]
	v_or_b32_e32 v244, v244, v48
	v_lshl_add_u64 v[154:155], v[244:245], 2, s[72:73]
	v_lshl_add_u64 v[162:163], v[244:245], 1, s[92:93]
	global_load_dwordx4 v[52:55], v[148:149], off
	global_load_dwordx4 v[56:59], v[148:149], off offset:16
	global_load_dwordx4 v[60:63], v[148:149], off offset:128
	global_load_dwordx4 v[64:67], v[148:149], off offset:144
	global_load_dwordx4 v[68:71], v[148:149], off offset:256
	global_load_dwordx4 v[72:75], v[148:149], off offset:272
	global_load_dwordx4 v[76:79], v[148:149], off offset:384
	global_load_dwordx4 v[80:83], v[148:149], off offset:400
	global_load_dwordx4 v[84:87], v[148:149], off offset:512
	global_load_dwordx4 v[88:91], v[148:149], off offset:528
	global_load_dwordx4 v[92:95], v[148:149], off offset:640
	global_load_dwordx4 v[96:99], v[148:149], off offset:656
	global_load_dwordx4 v[100:103], v[148:149], off offset:768
	global_load_dwordx4 v[104:107], v[148:149], off offset:784
	global_load_dwordx4 v[108:111], v[148:149], off offset:896
	global_load_dwordx4 v[112:115], v[148:149], off offset:912
	global_load_dwordx4 v[116:119], v[150:151], off
	global_load_dwordx4 v[120:123], v[150:151], off offset:16
	global_load_dwordx4 v[124:127], v[150:151], off offset:128
	global_load_dwordx4 v[128:131], v[150:151], off offset:144
	global_load_dwordx4 v[132:135], v[150:151], off offset:256
	global_load_dwordx4 v[136:139], v[150:151], off offset:272
	global_load_dwordx4 v[140:143], v[150:151], off offset:384
	global_load_dwordx4 v[144:147], v[150:151], off offset:400
	s_waitcnt vmcnt(22)
; __device__ __forceinline__ unsigned cvt_pk_bf16(float lo, float hi) { const f32x2v v = {lo, hi}; const b16x2v r = __builtin_convertvector(v, b16x2v); return __builtin_bit_cast(unsigned, r); }
; __device__ __forceinline__ f32x4 mfma16(bf16x8 a, bf16x8 b, f32x4 c) { return __builtin_amdgcn_mfma_f32_16x16x32_bf16(a, b, c, 0, 0, 0); }
; __device__ void prep_phase(const Params& p, unsigned char* smem_g) {
;     ...
;         for (int mt = 0; mt < 4; ++mt) {
;             acc[mt] = (f32x4){0.f, 0.f, 0.f, 0.f};
; #pragma unroll
;             for (int ks = 0; ks < 8; ++ks) {
;                 const size_t off = (size_t)(t0 + 16 * ((mt + mrot) & 3) + idx) * DM + 256 * wk + 32 * ks + 8 * g;
;                 const f32x4 a = *(const f32x4*)(p.x + off), b = *(const f32x4*)(p.x + off + 4);
;                 u32x4 w; w.x = cvt_pk_bf16(a[0], a[1]); w.y = cvt_pk_bf16(a[2], a[3]); w.z = cvt_pk_bf16(b[0], b[1]); w.w = cvt_pk_bf16(b[2], b[3]);
;                 *(u32x4*)(xb + off) = w;
;                 acc[mt] = mfma16(__builtin_bit_cast(bf16x8, w), bfr[ks], acc[mt]);
;             }
;         }
	v_cvt_pk_bf16_f32 v236, v52, v53
	v_cvt_pk_bf16_f32 v237, v54, v55
	v_cvt_pk_bf16_f32 v238, v56, v57
	v_cvt_pk_bf16_f32 v239, v58, v59
	global_store_dwordx4 v[156:157], v[236:239], off
	s_nop 0
	v_mfma_f32_16x16x32_bf16 v[36:39], v[236:239], v[32:35], 0
	global_load_dwordx4 v[52:55], v[150:151], off offset:512
	global_load_dwordx4 v[56:59], v[150:151], off offset:528
	s_waitcnt vmcnt(23)
	v_cvt_pk_bf16_f32 v240, v60, v61
	v_cvt_pk_bf16_f32 v241, v62, v63
	v_cvt_pk_bf16_f32 v242, v64, v65
	v_cvt_pk_bf16_f32 v243, v66, v67
	global_store_dwordx4 v[156:157], v[240:243], off offset:64
	s_nop 0
	v_mfma_f32_16x16x32_bf16 v[36:39], v[240:243], v[28:31], v[36:39]
	global_load_dwordx4 v[60:63], v[150:151], off offset:640
	global_load_dwordx4 v[64:67], v[150:151], off offset:656
	s_waitcnt vmcnt(24)
	v_cvt_pk_bf16_f32 v236, v68, v69
	v_cvt_pk_bf16_f32 v237, v70, v71
	v_cvt_pk_bf16_f32 v238, v72, v73
	v_cvt_pk_bf16_f32 v239, v74, v75
	global_store_dwordx4 v[156:157], v[236:239], off offset:128
	s_nop 0
	v_mfma_f32_16x16x32_bf16 v[36:39], v[236:239], v[24:27], v[36:39]
	global_load_dwordx4 v[68:71], v[150:151], off offset:768
	global_load_dwordx4 v[72:75], v[150:151], off offset:784
	s_waitcnt vmcnt(25)
	v_cvt_pk_bf16_f32 v240, v76, v77
	v_cvt_pk_bf16_f32 v241, v78, v79
	v_cvt_pk_bf16_f32 v242, v80, v81
	v_cvt_pk_bf16_f32 v243, v82, v83
	global_store_dwordx4 v[156:157], v[240:243], off offset:192
	s_nop 0
	v_mfma_f32_16x16x32_bf16 v[36:39], v[240:243], v[20:23], v[36:39]
	global_load_dwordx4 v[76:79], v[150:151], off offset:896
	global_load_dwordx4 v[80:83], v[150:151], off offset:912
	s_waitcnt vmcnt(26)
	v_cvt_pk_bf16_f32 v236, v84, v85
	v_cvt_pk_bf16_f32 v237, v86, v87
	v_cvt_pk_bf16_f32 v238, v88, v89
	v_cvt_pk_bf16_f32 v239, v90, v91
	global_store_dwordx4 v[156:157], v[236:239], off offset:256
	s_nop 0
	v_mfma_f32_16x16x32_bf16 v[36:39], v[236:239], v[16:19], v[36:39]
	global_load_dwordx4 v[84:87], v[152:153], off
	global_load_dwordx4 v[88:91], v[152:153], off offset:16
	s_waitcnt vmcnt(27)
	v_cvt_pk_bf16_f32 v240, v92, v93
	v_cvt_pk_bf16_f32 v241, v94, v95
	v_cvt_pk_bf16_f32 v242, v96, v97
	v_cvt_pk_bf16_f32 v243, v98, v99
	global_store_dwordx4 v[156:157], v[240:243], off offset:320
	s_nop 0
	v_mfma_f32_16x16x32_bf16 v[36:39], v[240:243], v[12:15], v[36:39]
	global_load_dwordx4 v[92:95], v[152:153], off offset:128
	global_load_dwordx4 v[96:99], v[152:153], off offset:144
	s_waitcnt vmcnt(28)
	v_cvt_pk_bf16_f32 v236, v100, v101
	v_cvt_pk_bf16_f32 v237, v102, v103
	v_cvt_pk_bf16_f32 v238, v104, v105
	v_cvt_pk_bf16_f32 v239, v106, v107
	global_store_dwordx4 v[156:157], v[236:239], off offset:384
	s_nop 0
	v_mfma_f32_16x16x32_bf16 v[36:39], v[236:239], v[8:11], v[36:39]
	global_load_dwordx4 v[100:103], v[152:153], off offset:256
	global_load_dwordx4 v[104:107], v[152:153], off offset:272
	s_waitcnt vmcnt(29)
	v_cvt_pk_bf16_f32 v240, v108, v109
	v_cvt_pk_bf16_f32 v241, v110, v111
	v_cvt_pk_bf16_f32 v242, v112, v113
	v_cvt_pk_bf16_f32 v243, v114, v115
	global_store_dwordx4 v[156:157], v[240:243], off offset:448
	s_nop 0
	v_mfma_f32_16x16x32_bf16 v[36:39], v[240:243], v[4:7], v[36:39]
	global_load_dwordx4 v[108:111], v[152:153], off offset:384
	global_load_dwordx4 v[112:115], v[152:153], off offset:400
	s_waitcnt vmcnt(30)
	v_cvt_pk_bf16_f32 v236, v116, v117
	v_cvt_pk_bf16_f32 v237, v118, v119
	v_cvt_pk_bf16_f32 v238, v120, v121
	v_cvt_pk_bf16_f32 v239, v122, v123
	global_store_dwordx4 v[158:159], v[236:239], off
	s_nop 0
	v_mfma_f32_16x16x32_bf16 v[40:43], v[236:239], v[32:35], 0
	global_load_dwordx4 v[116:119], v[152:153], off offset:512
	global_load_dwordx4 v[120:123], v[152:153], off offset:528
	s_waitcnt vmcnt(31)
	v_cvt_pk_bf16_f32 v240, v124, v125
	v_cvt_pk_bf16_f32 v241, v126, v127
	v_cvt_pk_bf16_f32 v242, v128, v129
	v_cvt_pk_bf16_f32 v243, v130, v131
	global_store_dwordx4 v[158:159], v[240:243], off offset:64
	s_nop 0
	v_mfma_f32_16x16x32_bf16 v[40:43], v[240:243], v[28:31], v[40:43]
	global_load_dwordx4 v[124:127], v[152:153], off offset:640
	global_load_dwordx4 v[128:131], v[152:153], off offset:656
	s_waitcnt vmcnt(32)
	v_cvt_pk_bf16_f32 v236, v132, v133
	v_cvt_pk_bf16_f32 v237, v134, v135
	v_cvt_pk_bf16_f32 v238, v136, v137
	v_cvt_pk_bf16_f32 v239, v138, v139
	global_store_dwordx4 v[158:159], v[236:239], off offset:128
	s_nop 0
	v_mfma_f32_16x16x32_bf16 v[40:43], v[236:239], v[24:27], v[40:43]
	global_load_dwordx4 v[132:135], v[152:153], off offset:768
	global_load_dwordx4 v[136:139], v[152:153], off offset:784
	s_waitcnt vmcnt(33)
	v_cvt_pk_bf16_f32 v240, v140, v141
	v_cvt_pk_bf16_f32 v241, v142, v143
	v_cvt_pk_bf16_f32 v242, v144, v145
	v_cvt_pk_bf16_f32 v243, v146, v147
	global_store_dwordx4 v[158:159], v[240:243], off offset:192
	s_nop 0
	v_mfma_f32_16x16x32_bf16 v[40:43], v[240:243], v[20:23], v[40:43]
	global_load_dwordx4 v[140:143], v[152:153], off offset:896
	global_load_dwordx4 v[144:147], v[152:153], off offset:912
	s_waitcnt vmcnt(33)
	v_cvt_pk_bf16_f32 v236, v52, v53
	v_cvt_pk_bf16_f32 v237, v54, v55
	v_cvt_pk_bf16_f32 v238, v56, v57
	v_cvt_pk_bf16_f32 v239, v58, v59
	global_store_dwordx4 v[158:159], v[236:239], off offset:256
	s_nop 0
	v_mfma_f32_16x16x32_bf16 v[40:43], v[236:239], v[16:19], v[40:43]
	global_load_dwordx4 v[52:55], v[154:155], off
	global_load_dwordx4 v[56:59], v[154:155], off offset:16
	s_waitcnt vmcnt(33)
	v_cvt_pk_bf16_f32 v240, v60, v61
	v_cvt_pk_bf16_f32 v241, v62, v63
	v_cvt_pk_bf16_f32 v242, v64, v65
	v_cvt_pk_bf16_f32 v243, v66, v67
	global_store_dwordx4 v[158:159], v[240:243], off offset:320
	s_nop 0
	v_mfma_f32_16x16x32_bf16 v[40:43], v[240:243], v[12:15], v[40:43]
	global_load_dwordx4 v[60:63], v[154:155], off offset:128
	global_load_dwordx4 v[64:67], v[154:155], off offset:144
	s_waitcnt vmcnt(33)
; __device__ __forceinline__ unsigned cvt_pk_bf16(float lo, float hi) { const f32x2v v = {lo, hi}; const b16x2v r = __builtin_convertvector(v, b16x2v); return __builtin_bit_cast(unsigned, r); }
; __device__ __forceinline__ f32x4 mfma16(bf16x8 a, bf16x8 b, f32x4 c) { return __builtin_amdgcn_mfma_f32_16x16x32_bf16(a, b, c, 0, 0, 0); }
; __device__ void prep_phase(const Params& p, unsigned char* smem_g) {
;     ...
;         for (int mt = 0; mt < 4; ++mt) {
;             acc[mt] = (f32x4){0.f, 0.f, 0.f, 0.f};
; #pragma unroll
;             for (int ks = 0; ks < 8; ++ks) {
;                 const size_t off = (size_t)(t0 + 16 * ((mt + mrot) & 3) + idx) * DM + 256 * wk + 32 * ks + 8 * g;
;                 const f32x4 a = *(const f32x4*)(p.x + off), b = *(const f32x4*)(p.x + off + 4);
;                 u32x4 w; w.x = cvt_pk_bf16(a[0], a[1]); w.y = cvt_pk_bf16(a[2], a[3]); w.z = cvt_pk_bf16(b[0], b[1]); w.w = cvt_pk_bf16(b[2], b[3]);
;                 *(u32x4*)(xb + off) = w;
;                 acc[mt] = mfma16(__builtin_bit_cast(bf16x8, w), bfr[ks], acc[mt]);
;             }
;         }
; #pragma unroll
;         for (int mt = 0; mt < 4; ++mt)
; #pragma unroll
;             for (int r = 0; r < 4; ++r) red[(wid * 64 + 16 * ((mt + mrot) & 3) + 4 * g + r) * 16 + idx] = acc[mt][r];
	v_cvt_pk_bf16_f32 v236, v68, v69
	v_cvt_pk_bf16_f32 v237, v70, v71
	v_cvt_pk_bf16_f32 v238, v72, v73
	v_cvt_pk_bf16_f32 v239, v74, v75
	global_store_dwordx4 v[158:159], v[236:239], off offset:384
	s_nop 0
	v_mfma_f32_16x16x32_bf16 v[40:43], v[236:239], v[8:11], v[40:43]
	global_load_dwordx4 v[68:71], v[154:155], off offset:256
	global_load_dwordx4 v[72:75], v[154:155], off offset:272
	s_waitcnt vmcnt(33)
	v_cvt_pk_bf16_f32 v240, v76, v77
	v_cvt_pk_bf16_f32 v241, v78, v79
	v_cvt_pk_bf16_f32 v242, v80, v81
	v_cvt_pk_bf16_f32 v243, v82, v83
	global_store_dwordx4 v[158:159], v[240:243], off offset:448
	s_nop 0
	v_mfma_f32_16x16x32_bf16 v[40:43], v[240:243], v[4:7], v[40:43]
	global_load_dwordx4 v[76:79], v[154:155], off offset:384
	global_load_dwordx4 v[80:83], v[154:155], off offset:400
	s_waitcnt vmcnt(33)
	v_cvt_pk_bf16_f32 v236, v84, v85
	v_cvt_pk_bf16_f32 v237, v86, v87
	v_cvt_pk_bf16_f32 v238, v88, v89
	v_cvt_pk_bf16_f32 v239, v90, v91
	global_store_dwordx4 v[160:161], v[236:239], off
	s_nop 0
	v_mfma_f32_16x16x32_bf16 v[44:47], v[236:239], v[32:35], 0
	global_load_dwordx4 v[84:87], v[154:155], off offset:512
	global_load_dwordx4 v[88:91], v[154:155], off offset:528
	s_waitcnt vmcnt(33)
	v_cvt_pk_bf16_f32 v240, v92, v93
	v_cvt_pk_bf16_f32 v241, v94, v95
	v_cvt_pk_bf16_f32 v242, v96, v97
	v_cvt_pk_bf16_f32 v243, v98, v99
	global_store_dwordx4 v[160:161], v[240:243], off offset:64
	s_nop 0
	v_mfma_f32_16x16x32_bf16 v[44:47], v[240:243], v[28:31], v[44:47]
	global_load_dwordx4 v[92:95], v[154:155], off offset:640
	global_load_dwordx4 v[96:99], v[154:155], off offset:656
	s_waitcnt vmcnt(33)
	v_cvt_pk_bf16_f32 v236, v100, v101
	v_cvt_pk_bf16_f32 v237, v102, v103
	v_cvt_pk_bf16_f32 v238, v104, v105
	v_cvt_pk_bf16_f32 v239, v106, v107
	global_store_dwordx4 v[160:161], v[236:239], off offset:128
	s_nop 0
	v_mfma_f32_16x16x32_bf16 v[44:47], v[236:239], v[24:27], v[44:47]
	global_load_dwordx4 v[100:103], v[154:155], off offset:768
	global_load_dwordx4 v[104:107], v[154:155], off offset:784
	s_waitcnt vmcnt(33)
	v_cvt_pk_bf16_f32 v240, v108, v109
	v_cvt_pk_bf16_f32 v241, v110, v111
	v_cvt_pk_bf16_f32 v242, v112, v113
	v_cvt_pk_bf16_f32 v243, v114, v115
	global_store_dwordx4 v[160:161], v[240:243], off offset:192
	s_nop 0
	v_mfma_f32_16x16x32_bf16 v[44:47], v[240:243], v[20:23], v[44:47]
	global_load_dwordx4 v[108:111], v[154:155], off offset:896
	global_load_dwordx4 v[112:115], v[154:155], off offset:912
	s_waitcnt vmcnt(33)
	v_cvt_pk_bf16_f32 v236, v116, v117
	v_cvt_pk_bf16_f32 v237, v118, v119
	v_cvt_pk_bf16_f32 v238, v120, v121
	v_cvt_pk_bf16_f32 v239, v122, v123
	global_store_dwordx4 v[160:161], v[236:239], off offset:256
	s_nop 0
	v_mfma_f32_16x16x32_bf16 v[44:47], v[236:239], v[16:19], v[44:47]
	s_waitcnt vmcnt(31)
	v_cvt_pk_bf16_f32 v240, v124, v125
	v_cvt_pk_bf16_f32 v241, v126, v127
	v_cvt_pk_bf16_f32 v242, v128, v129
	v_cvt_pk_bf16_f32 v243, v130, v131
	global_store_dwordx4 v[160:161], v[240:243], off offset:320
	s_nop 0
	v_mfma_f32_16x16x32_bf16 v[44:47], v[240:243], v[12:15], v[44:47]
	s_waitcnt vmcnt(29)
	v_cvt_pk_bf16_f32 v236, v132, v133
	v_cvt_pk_bf16_f32 v237, v134, v135
	v_cvt_pk_bf16_f32 v238, v136, v137
	v_cvt_pk_bf16_f32 v239, v138, v139
	global_store_dwordx4 v[160:161], v[236:239], off offset:384
	s_nop 0
	v_mfma_f32_16x16x32_bf16 v[44:47], v[236:239], v[8:11], v[44:47]
	s_waitcnt vmcnt(27)
	v_cvt_pk_bf16_f32 v240, v140, v141
	v_cvt_pk_bf16_f32 v241, v142, v143
	v_cvt_pk_bf16_f32 v242, v144, v145
	v_cvt_pk_bf16_f32 v243, v146, v147
	global_store_dwordx4 v[160:161], v[240:243], off offset:448
	s_nop 0
	v_mfma_f32_16x16x32_bf16 v[44:47], v[240:243], v[4:7], v[44:47]
	s_waitcnt vmcnt(25)
	v_cvt_pk_bf16_f32 v236, v52, v53
	v_cvt_pk_bf16_f32 v237, v54, v55
	v_cvt_pk_bf16_f32 v238, v56, v57
	v_cvt_pk_bf16_f32 v239, v58, v59
	global_store_dwordx4 v[162:163], v[236:239], off
	s_nop 0
	v_mfma_f32_16x16x32_bf16 v[164:167], v[236:239], v[32:35], 0
	s_waitcnt vmcnt(23)
	v_cvt_pk_bf16_f32 v240, v60, v61
	v_cvt_pk_bf16_f32 v241, v62, v63
	v_cvt_pk_bf16_f32 v242, v64, v65
	v_cvt_pk_bf16_f32 v243, v66, v67
	global_store_dwordx4 v[162:163], v[240:243], off offset:64
	s_nop 0
	v_mfma_f32_16x16x32_bf16 v[164:167], v[240:243], v[28:31], v[164:167]
	s_waitcnt vmcnt(21)
	v_cvt_pk_bf16_f32 v236, v68, v69
	v_cvt_pk_bf16_f32 v237, v70, v71
	v_cvt_pk_bf16_f32 v238, v72, v73
	v_cvt_pk_bf16_f32 v239, v74, v75
	global_store_dwordx4 v[162:163], v[236:239], off offset:128
	s_nop 0
	v_mfma_f32_16x16x32_bf16 v[164:167], v[236:239], v[24:27], v[164:167]
	s_waitcnt vmcnt(19)
	v_cvt_pk_bf16_f32 v240, v76, v77
	v_cvt_pk_bf16_f32 v241, v78, v79
	v_cvt_pk_bf16_f32 v242, v80, v81
	v_cvt_pk_bf16_f32 v243, v82, v83
	global_store_dwordx4 v[162:163], v[240:243], off offset:192
	s_nop 0
	v_mfma_f32_16x16x32_bf16 v[164:167], v[240:243], v[20:23], v[164:167]
	s_waitcnt vmcnt(17)
	v_cvt_pk_bf16_f32 v236, v84, v85
	v_cvt_pk_bf16_f32 v237, v86, v87
	v_cvt_pk_bf16_f32 v238, v88, v89
	v_cvt_pk_bf16_f32 v239, v90, v91
	global_store_dwordx4 v[162:163], v[236:239], off offset:256
	s_nop 0
	v_mfma_f32_16x16x32_bf16 v[164:167], v[236:239], v[16:19], v[164:167]
	s_waitcnt vmcnt(15)
	v_cvt_pk_bf16_f32 v240, v92, v93
	v_cvt_pk_bf16_f32 v241, v94, v95
	v_cvt_pk_bf16_f32 v242, v96, v97
	v_cvt_pk_bf16_f32 v243, v98, v99
	global_store_dwordx4 v[162:163], v[240:243], off offset:320
	s_nop 0
	v_mfma_f32_16x16x32_bf16 v[164:167], v[240:243], v[12:15], v[164:167]
	s_waitcnt vmcnt(13)
	v_cvt_pk_bf16_f32 v236, v100, v101
	v_cvt_pk_bf16_f32 v237, v102, v103
	v_cvt_pk_bf16_f32 v238, v104, v105
	v_cvt_pk_bf16_f32 v239, v106, v107
	global_store_dwordx4 v[162:163], v[236:239], off offset:384
	s_nop 0
	v_mfma_f32_16x16x32_bf16 v[164:167], v[236:239], v[8:11], v[164:167]
	s_waitcnt vmcnt(11)
	v_cvt_pk_bf16_f32 v240, v108, v109
	v_cvt_pk_bf16_f32 v241, v110, v111
	v_cvt_pk_bf16_f32 v242, v112, v113
	v_cvt_pk_bf16_f32 v243, v114, v115
	global_store_dwordx4 v[162:163], v[240:243], off offset:448
	s_nop 0
	v_mfma_f32_16x16x32_bf16 v[164:167], v[240:243], v[4:7], v[164:167]
	v_mov_b32_e32 v21, 0
	s_nop 4
	ds_write2_b32 v2, v36, v37 offset1:16
	ds_write2_b32 v2, v38, v39 offset0:32 offset1:48
	ds_write2_b32 v232, v40, v41 offset1:16
	ds_write2_b32 v232, v42, v43 offset0:32 offset1:48
	ds_write2_b32 v233, v44, v45 offset1:16
	ds_write2_b32 v233, v46, v47 offset0:32 offset1:48
	s_nop 1
	ds_write2_b32 v235, v164, v165 offset1:16
	ds_write2_b32 v235, v166, v167 offset0:32 offset1:48
	s_waitcnt lgkmcnt(0)
	s_barrier
; __device__ void prep_phase(const Params& p, unsigned char* smem_g) {
;     ...
;         __syncthreads();
;         { const int tok = tid >> 3, c2 = (tid & 7) * 2; float s0 = 0.f, s1 = 0.f;
; #pragma unroll
;           for (int w = 0; w < 8; ++w) { s0 += red[(w * 64 + tok) * 16 + c2]; s1 += red[(w * 64 + tok) * 16 + c2 + 1]; }
;           glrs[tok * 16 + c2] = s0; glrs[tok * 16 + c2 + 1] = s1; }
;         __syncthreads();
;         { const int c = tid; float w2c[16];
; #pragma unroll
;           for (int r = 0; r < 16; ++r) w2c[r] = p.gate_w2[r * 512 + c];
;           const float bias = p.gate_b[c]; float b2 = 0.f;
	ds_read2st64_b64 v[4:7], v1 offset1:8
	s_waitcnt lgkmcnt(0)
	v_pk_add_f32 v[4:5], v[4:5], 0 op_sel_hi:[1,0]
	s_nop 0
	v_pk_add_f32 v[8:9], v[4:5], v[6:7]
	ds_read2st64_b64 v[4:7], v1 offset0:16 offset1:24
	s_waitcnt lgkmcnt(0)
	v_pk_add_f32 v[4:5], v[8:9], v[4:5]
	s_nop 0
	v_pk_add_f32 v[8:9], v[4:5], v[6:7]
	ds_read2st64_b64 v[4:7], v1 offset0:32 offset1:40
	s_waitcnt lgkmcnt(0)
	v_pk_add_f32 v[4:5], v[8:9], v[4:5]
	s_nop 0
	v_pk_add_f32 v[8:9], v[4:5], v[6:7]
	ds_read2st64_b64 v[4:7], v1 offset0:48 offset1:56
	s_waitcnt lgkmcnt(0)
	v_pk_add_f32 v[4:5], v[8:9], v[4:5]
	s_nop 0
	v_pk_add_f32 v[4:5], v[4:5], v[6:7]
	ds_write_b64 v1, v[4:5] offset:32768
	s_waitcnt lgkmcnt(0)
	s_barrier
	global_load_dword v4, v[180:181], off
	global_load_dword v6, v[180:181], off offset:2048
	global_load_dword v8, v[182:183], off
	global_load_dword v10, v[186:187], off
	global_load_dword v5, v[188:189], off
	global_load_dword v7, v[190:191], off
	global_load_dword v9, v[192:193], off
	global_load_dword v11, v[194:195], off
	global_load_dword v12, v[196:197], off
	global_load_dword v14, v[198:199], off
	global_load_dword v16, v[200:201], off
	global_load_dword v18, v[202:203], off
	global_load_dword v13, v[204:205], off
	global_load_dword v15, v[206:207], off
	global_load_dword v17, v[208:209], off
	global_load_dword v19, v[210:211], off
	global_load_dword v20, v[184:185], off
	s_waitcnt vmcnt(0)
